# per-XCD attention queues: NSA bg pinned to XCD, fox rotated across XCDs
# speedup vs baseline: 1.1463x; 1.0018x over previous
; DI int pop_item(int* ctr, int* slot) {
;   __syncthreads();
;   if (threadIdx.x == 0) *slot = atomicAdd(ctr, 1);
;   __syncthreads();
;   return *slot;
; }
.LBB0_631:
	s_barrier
	s_and_saveexec_b64 s[0:1], s[26:27]
	s_cbranch_execz .LBB0_635
	s_mov_b64 s[4:5], exec
	v_mbcnt_lo_u32_b32 v0, s4, 0
	v_mbcnt_hi_u32_b32 v0, s5, v0
	v_cmp_eq_u32_e32 vcc, 0, v0
	s_and_saveexec_b64 s[2:3], vcc
	s_cbranch_execz .LBB0_634
	s_bcnt1_i32_b64 s4, s[4:5]
	v_mov_b32_e32 v2, s4
	v_readlane_b32 s4, v253, 36
	s_and_b32 s4, s4, 7
	s_lshl_b32 s4, s4, 4
	s_add_i32 s4, s4, 20
	v_mov_b32_e32 v4, s4
	v_readlane_b32 s4, v254, 7
	v_readlane_b32 s5, v254, 8
	s_nop 4
	global_atomic_add v2, v4, v2, s[4:5] sc0

; DI int TID() { int t = threadIdx.x; asm volatile("" : "+v"(t)); return t; }
; DI void fox_item(const Params& p, int l_, int item, char* lds, int dry) {
;   const int qb = 15 - (item >> 5), bh = item & 31, b = bh >> 3, hd = bh & 7;
;   const int tid = TID(), lane = tid & 63, w = tid >> 6, r = lane & 31, h = lane >> 5;
;   const int wq0 = qb * 256 + w * 64;
;   const int qpos[2] = {wq0 + r, wq0 + 32 + r};
;   u16* zb = p.z + (size_t)b * S_ * ZS;
;   bf16x8 qf[2][4];
; #pragma unroll
;   for (int nb = 0; nb < 2; ++nb)
; #pragma unroll
;     for (int ks = 0; ks < 4; ++ks)
;       qf[nb][ks] = *(const bf16x8*)(zb + (size_t)qpos[nb] * ZS + QA + hd * 64 + ks * 16 + 8 * h);
;   const float* cb = p.cbuf + (size_t)(b * 8 + hd) * S_;
;   const float cq[2] = {cb[qpos[0]], cb[qpos[1]]};
; __global__ void __launch_bounds__(256, 2) hybrid_fwd(Params p) {
;     ...
;         for (;;) {
;           const int it = pop_item(ctr, &slot);
;           if (it >= 1024) break;
;           if (it < 512) { if (!dry || (P3_MASK & 1)) nsa_item(p, l, it, lds, dry); }
;           else { if (!dry || (P3_MASK & 2)) fox_item(p, l, it - 512, lds, dry); }
.LBB0_635:
	s_or_b64 exec, exec, s[0:1]
	s_waitcnt lgkmcnt(0)
	s_barrier
	ds_read_b32 v0, v221
	s_movk_i32 s0, 0x80
	s_waitcnt lgkmcnt(0)
	v_cmp_gt_i32_e32 vcc, s0, v0
	v_readfirstlane_b32 s16, v0
	s_mov_b64 s[0:1], -1
	s_cbranch_vccz .LBB0_630
	v_readlane_b32 s2, v253, 36
	s_and_b32 s2, s2, 7
	s_cmpk_gt_i32 s16, 63
	s_cbranch_scc1 .Lq_fox
	s_lshl_b32 s16, s16, 3
	s_or_b32 s16, s16, s2
	s_branch .LBB0_665
.Lq_fox:
	s_sub_i32 s1, s16, 64
	s_and_b32 s3, s1, 3
	s_lshr_b32 s1, s1, 2
	s_add_i32 s2, s2, s1
	s_and_b32 s2, s2, 7
	s_lshl_b32 s3, s3, 3
	s_or_b32 s2, s2, s3
	s_lshl_b32 s1, s1, 5
	s_or_b32 s2, s2, s1
	s_add_i32 s16, s2, 0x200
	s_add_i32 s6, s16, 0xfffffe00
	s_lshr_b32 s8, s6, 5
	s_bfe_u32 s0, s16, 0x20003
	s_lshl_b32 s1, s8, 8
	v_readlane_b32 s80, v253, 12
	s_xor_b32 s17, s1, 0xf00
	s_mul_i32 s0, s0, 0x3300000
	v_readlane_b32 s86, v253, 18
	v_readlane_b32 s87, v253, 19
	s_add_u32 s2, s86, s0
	s_addc_u32 s3, s87, 0
	s_lshl_b32 s0, s6, 6
	v_mov_b32_e32 v2, v209
	s_and_b32 s0, s0, 0x1c0
	s_lshl_b32 s18, s0, 1
	v_and_b32_e32 v0, 0xffffffc0, v2
	v_bfe_u32 v210, v2, 5, 1
	v_add_u32_e32 v232, s17, v0
	s_add_u32 s4, s2, s18
	v_and_or_b32 v214, v2, 31, v232
	s_addc_u32 s5, s3, 0
	v_lshlrev_b32_e32 v0, 4, v210
	v_or_b32_e32 v233, 32, v214
	v_lshl_add_u64 v[4:5], s[4:5], 0, v[0:1]
	v_mad_i64_i32 v[6:7], s[0:1], v214, s75, v[4:5]
	v_mad_i64_i32 v[4:5], s[0:1], v233, s75, v[4:5]
	s_lshl_b32 s0, s6, 14
	v_readlane_b32 s36, v251, 34
	s_and_b32 s0, s0, 0x7c000
	v_readlane_b32 s38, v251, 36
	v_readlane_b32 s39, v251, 37
	s_add_u32 s6, s38, s0
	v_ashrrev_i32_e32 v215, 31, v214
	s_addc_u32 s7, s39, 0
	s_lshl_b32 s8, s8, 2
	s_mov_b64 s[52:53], s[18:19]
	global_load_dwordx4 v[144:147], v[6:7], off
	global_load_dwordx4 v[148:151], v[6:7], off offset:32
	global_load_dwordx4 v[152:155], v[6:7], off offset:64
	global_load_dwordx4 v[156:159], v[6:7], off offset:96
	global_load_dwordx4 v[160:163], v[4:5], off
	global_load_dwordx4 v[164:167], v[4:5], off offset:32
	global_load_dwordx4 v[168:171], v[4:5], off offset:64
	global_load_dwordx4 v[172:175], v[4:5], off offset:96
	v_lshl_add_u64 v[4:5], v[214:215], 2, s[6:7]
	v_mov_b32_e32 v215, v209
	s_xor_b32 s18, s8, 63
	global_load_dword v80, v[4:5], off
	global_load_dword v82, v[4:5], off offset:128
	s_lshl_b32 s9, s18, 6
	v_ashrrev_i32_e32 v234, 3, v215
	v_add_u32_e32 v0, s9, v234
	v_lshlrev_b32_e32 v3, 3, v215
	v_mul_lo_u32 v0, v0, s54
	v_and_b32_e32 v235, 56, v3
	v_or_b32_e32 v0, v0, v235
	v_add_u32_e32 v4, 0x33000, v0
	v_lshl_add_u64 v[6:7], v[0:1], 1, s[4:5]
	v_mov_b32_e32 v5, v1
	v_lshl_add_u64 v[4:5], v[4:5], 1, s[4:5]
	global_load_dwordx4 v[176:179], v[6:7], off offset:1024
	global_load_dwordx4 v[180:183], v[6:7], off offset:2048
	global_load_dwordx4 v[184:187], v[4:5], off offset:1024
	global_load_dwordx4 v[188:191], v[4:5], off offset:2048
	v_readlane_b32 s42, v251, 40
	v_readlane_b32 s43, v251, 41
	v_cmp_gt_i32_e64 s[42:43], 64, v215
	v_mov_b32_e32 v236, 0
	v_readlane_b32 s81, v253, 13
	v_readlane_b32 s82, v253, 14
	v_readlane_b32 s83, v253, 15
	v_readlane_b32 s84, v253, 16
	v_readlane_b32 s85, v253, 17
	v_readlane_b32 s88, v253, 20
	v_readlane_b32 s89, v253, 21
	v_readlane_b32 s90, v253, 22
	v_readlane_b32 s91, v253, 23
	v_readlane_b32 s92, v253, 24
	v_readlane_b32 s93, v253, 25
	v_readlane_b32 s94, v253, 26
	v_readlane_b32 s95, v253, 27
	v_readlane_b32 s37, v251, 35
	v_readlane_b32 s40, v251, 38
	v_readlane_b32 s41, v251, 39
	v_readlane_b32 s44, v251, 42
	v_readlane_b32 s45, v251, 43
	v_readlane_b32 s46, v251, 44
	v_readlane_b32 s47, v251, 45
	v_readlane_b32 s48, v251, 46
	v_readlane_b32 s49, v251, 47
	v_readlane_b32 s50, v251, 48
	v_readlane_b32 s51, v251, 49
	s_and_saveexec_b64 s[0:1], s[42:43]
	s_cbranch_execz .LBB0_639
	v_add_u32_e32 v4, s9, v215
	v_ashrrev_i32_e32 v5, 31, v4
	v_lshl_add_u64 v[4:5], v[4:5], 2, s[6:7]
	global_load_dword v236, v[4:5], off
